# weight-conversion completion wait: dropped the redundant L1 invalidate (the L1 cannot hold those lines)
# baseline (speedup 1.0000x reference)
.LBB0_664:
	global_load_dword v0, v177, s[6:7] sc1
	s_mov_b64 s[0:1], -1
	s_waitcnt vmcnt(0)
	v_cmp_le_u32_e32 vcc, s86, v0
	s_cbranch_vccnz .LBB0_663
	s_sleep 1
	global_load_dword v0, v177, s[6:7] sc1
	s_waitcnt vmcnt(0)
	v_cmp_gt_u32_e32 vcc, s86, v0
	s_cbranch_vccz .LBB0_663
	s_sleep 1
	global_load_dword v0, v177, s[6:7] sc1
	s_waitcnt vmcnt(0)
	v_cmp_gt_u32_e32 vcc, s86, v0
	s_cbranch_vccz .LBB0_663
	s_sleep 1
	global_load_dword v0, v177, s[6:7] sc1
	s_waitcnt vmcnt(0)
	v_cmp_gt_u32_e32 vcc, s86, v0
	s_cbranch_vccz .LBB0_663
	s_sleep 1
	global_load_dword v0, v177, s[6:7] sc1
	s_waitcnt vmcnt(0)
	v_cmp_gt_u32_e32 vcc, s86, v0
	s_cbranch_vccz .LBB0_663
	s_add_i32 s8, s8, -5
	s_cmp_eq_u32 s8, 0
	s_cselect_b64 s[0:1], -1, 0
	s_sleep 1
	s_branch .LBB0_663
.LBB0_670:
	s_waitcnt vmcnt(0)
.LBB0_671:
	s_or_b64 exec, exec, s[2:3]
	s_barrier

.LBB0_775:
	global_load_dword v0, v177, s[6:7] sc1
	s_mov_b64 s[0:1], -1
	s_waitcnt vmcnt(0)
	v_cmp_le_u32_e32 vcc, s86, v0
	s_cbranch_vccnz .LBB0_774
	s_sleep 1
	global_load_dword v0, v177, s[6:7] sc1
	s_waitcnt vmcnt(0)
	v_cmp_gt_u32_e32 vcc, s86, v0
	s_cbranch_vccz .LBB0_774
	s_sleep 1
	global_load_dword v0, v177, s[6:7] sc1
	s_waitcnt vmcnt(0)
	v_cmp_gt_u32_e32 vcc, s86, v0
	s_cbranch_vccz .LBB0_774
	s_sleep 1
	global_load_dword v0, v177, s[6:7] sc1
	s_waitcnt vmcnt(0)
	v_cmp_gt_u32_e32 vcc, s86, v0
	s_cbranch_vccz .LBB0_774
	s_sleep 1
	global_load_dword v0, v177, s[6:7] sc1
	s_waitcnt vmcnt(0)
	v_cmp_gt_u32_e32 vcc, s86, v0
	s_cbranch_vccz .LBB0_774
	s_add_i32 s8, s8, -5
	s_cmp_eq_u32 s8, 0
	s_cselect_b64 s[0:1], -1, 0
	s_sleep 1
	s_branch .LBB0_774
.LBB0_781:
	s_waitcnt vmcnt(0)
.LBB0_782:
	s_or_b64 exec, exec, s[4:5]
	s_barrier
